# scan: X-init and Y products with the contraction packed over all four lane groups (2 f32 MFMAs each instead of 4, permlane32_swap builds the SA operand)
# speedup vs baseline: 1.0262x; 1.0171x over previous
.Lmy_ck_nz:
	s_mov_b32 s100, 0xe000
	s_cmp_eq_u32 s23, 0
	s_cselect_b32 s100, 0x1c000, s100
	v_lshl_add_u32 v236, v224, 4, s100
	v_xor_b32_e32 v225, v224, v234
	v_lshl_add_u32 v225, v225, 4, s100
	s_add_i32 s101, s100, 0x2000
	v_lshl_add_u32 v226, v234, 4, s101
	s_add_i32 s101, s100, 0x2600
	v_mov_b32_e32 v72, s101
	v_cmp_eq_u32_e64 s[96:97], 0, v234
	s_add_i32 s101, s100, 0x2500
	v_mov_b32_e32 v73, s101
	s_add_i32 s101, s100, 0x2510
	v_mov_b32_e32 v74, s101
	v_cndmask_b32_e64 v227, v72, v73, s[96:97]
	v_cmp_eq_u32_e64 s[96:97], 1, v234
	s_add_i32 s101, s100, 0x2590
	v_mov_b32_e32 v75, s101
	v_and_b32_e32 v76, 1, v234
	v_cndmask_b32_e64 v228, v72, v74, s[96:97]
	v_cndmask_b32_e64 v229, v72, v75, s[96:97]
	v_lshlrev_b32_e32 v76, 10, v76
	v_lshl_add_u32 v76, v233, 2, v76
	v_add_u32_e32 v76, s62, v76
	s_lshl_b32 s96, s23, 13
	s_add_i32 s96, s96, 0xa000
	v_add_u32_e32 v230, s96, v76
	v_lshlrev_b32_e32 v77, 9, v234
	v_lshl_add_u32 v77, v233, 2, v77
	v_add_u32_e32 v77, s62, v77
	v_add_u32_e32 v239, s96, v77
	v_lshrrev_b32_e32 v77, 1, v234
	v_and_b32_e32 v78, 1, v234
	v_add_u32_e32 v79, 2, v77
	v_lshl_add_u32 v237, v79, 4, v233
	v_xor_b32_e32 v237, v237, v79
	v_lshlrev_b32_e32 v237, 4, v237
	v_lshl_add_u32 v237, v78, 3, v237
	s_add_i32 s101, s100, 0x2100
	v_add_u32_e32 v237, s101, v237
	v_lshl_add_u32 v238, v78, 4, v233
	v_xor_b32_e32 v238, v238, v78
	v_lshlrev_b32_e32 v238, 4, v238
	v_lshl_add_u32 v238, v77, 3, v238
	v_add_u32_e32 v238, s101, v238
	s_lshl_b32 s96, s23, 13
	s_add_i32 s96, s96, 0x18000
	v_add_u32_e32 v231, s96, v76
	v_add_u32_e32 v232, 48, v224
	v_and_b32_e32 v232, 63, v232
	v_lshlrev_b32_e32 v232, 2, v232
	s_mov_b32 s100, 0x6100
	s_cmp_eq_u32 s23, 0
	s_cselect_b32 s100, s100, 0x4e00
	v_add_u32_e32 v26, s100, v225
	v_add_u32_e32 v27, s100, v236
	v_add_u32_e32 v28, s100, v226
	v_add_u32_e32 v29, s100, v227
	v_add_u32_e32 v30, s100, v228
	v_add_u32_e32 v31, s100, v229
	v_add_u32_e32 v32, s100, v237
	v_add_u32_e32 v33, s100, v238
	ds_read_b64 v[80:81], v237
	ds_read_b64 v[82:83], v238
	ds_read_b32 v84, v230
	ds_read_b32 v85, v230 offset:256
	ds_read_b32 v86, v230 offset:512
	ds_read_b32 v87, v230 offset:768
	ds_read_b32 v36, v239
	ds_read_b32 v37, v239 offset:256
	ds_read_b128 v[88:91], v225
	ds_read_b128 v[92:95], v225 offset:1024
	ds_read_b128 v[96:99], v225 offset:2048
	ds_read_b128 v[100:103], v225 offset:3072
	ds_read_b32 v104, v227 offset:4
	ds_read_b32 v105, v227 offset:76
	ds_read_b64 v[106:107], v227 offset:8
	ds_read_b64 v[108:109], v227 offset:40
	ds_read_b32 v126, v229 offset:4
	ds_read_b32 v127, v229 offset:76
	ds_read_b64 v[128:129], v229 offset:8
	ds_read_b64 v[130:131], v229 offset:40
	ds_read_b64 v[110:111], v228
	ds_read_b64 v[112:113], v228 offset:32
	ds_read_b64 v[114:115], v228 offset:64
	ds_read_b64 v[116:117], v228 offset:96
	ds_read_b64 v[118:119], v228 offset:8
	ds_read_b64 v[120:121], v228 offset:40
	ds_read_b64 v[122:123], v228 offset:72
	ds_read_b64 v[124:125], v228 offset:104
	s_waitcnt lgkmcnt(15)
	v_mfma_f32_16x16x4_f32 v[240:243], v80, v36, 0
	v_mfma_f32_16x16x4_f32 v[240:243], v81, v37, v[240:243]
	v_mfma_f32_16x16x4_f32 v[240:243], v88, v208, v[240:243]
	ds_read_b128 v[184:187], v236 offset:4096
	ds_read_b128 v[188:191], v236 offset:5120
	v_mfma_f32_16x16x4_f32 v[244:247], v89, v209, 0
	ds_read_b128 v[192:195], v236 offset:6144
	ds_read_b128 v[196:199], v236 offset:7168
	v_mfma_f32_16x16x4_f32 v[240:243], v90, v210, v[240:243]
	ds_read_b64 v[132:133], v237 offset:9984
	ds_read_b64 v[134:135], v238 offset:9984
	v_mfma_f32_16x16x4_f32 v[244:247], v91, v211, v[244:247]
	ds_read_b32 v136, v230 offset:2048
	ds_read_b32 v137, v230 offset:2304
	v_mfma_f32_16x16x4_f32 v[240:243], v92, v212, v[240:243]
	ds_read_b32 v138, v230 offset:2560
	ds_read_b32 v139, v230 offset:2816
	v_mfma_f32_16x16x4_f32 v[244:247], v93, v213, v[244:247]
	ds_read_b32 v38, v239 offset:2048
	ds_read_b32 v39, v239 offset:2304
	v_mfma_f32_16x16x4_f32 v[240:243], v94, v214, v[240:243]
	ds_read_b128 v[140:143], v225 offset:9984
	ds_read_b128 v[144:147], v225 offset:11008
	v_mfma_f32_16x16x4_f32 v[244:247], v95, v215, v[244:247]
	ds_read_b128 v[148:151], v225 offset:12032
	ds_read_b128 v[152:155], v225 offset:13056
	v_mfma_f32_16x16x4_f32 v[240:243], v96, v216, v[240:243]
	ds_read_b32 v156, v227 offset:9988
	ds_read_b32 v157, v227 offset:10060
	v_mfma_f32_16x16x4_f32 v[244:247], v97, v217, v[244:247]
	ds_read_b64 v[158:159], v227 offset:9992
	ds_read_b64 v[160:161], v227 offset:10024
	v_mfma_f32_16x16x4_f32 v[240:243], v98, v218, v[240:243]
	ds_read_b32 v178, v229 offset:9988
	ds_read_b32 v179, v229 offset:10060
	v_mfma_f32_16x16x4_f32 v[244:247], v99, v219, v[244:247]
	ds_read_b64 v[180:181], v229 offset:9992
	ds_read_b64 v[182:183], v229 offset:10024
	v_mfma_f32_16x16x4_f32 v[240:243], v100, v220, v[240:243]
	ds_read_b64 v[162:163], v228 offset:9984
	ds_read_b64 v[164:165], v228 offset:10016
	v_mfma_f32_16x16x4_f32 v[244:247], v101, v221, v[244:247]
	ds_read_b64 v[166:167], v228 offset:10048
	ds_read_b64 v[168:169], v228 offset:10080
	v_mfma_f32_16x16x4_f32 v[240:243], v102, v222, v[240:243]
	ds_read_b64 v[170:171], v228 offset:9992
	ds_read_b64 v[172:173], v228 offset:10024
	v_mfma_f32_16x16x4_f32 v[244:247], v103, v223, v[244:247]
	ds_read_b64 v[174:175], v228 offset:10056
	ds_read_b64 v[176:177], v228 offset:10088
	s_nop 7
	v_pk_add_f32 v[240:241], v[240:241], v[244:245]
	v_pk_add_f32 v[242:243], v[242:243], v[246:247]
	v_fmac_f32_e32 v241, v104, v240
	s_waitcnt lgkmcnt(15)
	v_pk_fma_f32 v[242:243], v[106:107], v[240:241], v[242:243] op_sel:[0,0,0] op_sel_hi:[1,0,1]
	v_pk_fma_f32 v[242:243], v[108:109], v[240:241], v[242:243] op_sel:[0,1,0] op_sel_hi:[1,1,1]
	v_fmac_f32_e32 v243, v105, v242
	ds_bpermute_b32 v204, v232, v240
	ds_bpermute_b32 v205, v232, v241
	ds_bpermute_b32 v206, v232, v242
	ds_bpermute_b32 v207, v232, v243
	ds_read_b128 v[88:91], v226
	ds_read_b128 v[92:95], v226 offset:64
	ds_read_b128 v[96:99], v226 offset:128
	ds_read_b128 v[100:103], v226 offset:192
	v_mfma_f32_16x16x4_f32 v[72:75], v132, v38, 0
	v_mfma_f32_16x16x4_f32 v[72:75], v133, v39, v[72:75]
	s_waitcnt lgkmcnt(6)
	v_pk_fma_f32 v[240:241], v[110:111], v[204:205], v[240:241] op_sel:[0,0,0] op_sel_hi:[1,0,1]
	v_pk_fma_f32 v[240:241], v[112:113], v[204:205], v[240:241] op_sel:[0,1,0] op_sel_hi:[1,1,1]
	s_waitcnt lgkmcnt(4)
	v_pk_fma_f32 v[240:241], v[114:115], v[206:207], v[240:241] op_sel:[0,0,0] op_sel_hi:[1,0,1]
	v_pk_fma_f32 v[240:241], v[116:117], v[206:207], v[240:241] op_sel:[0,1,0] op_sel_hi:[1,1,1]
	v_pk_fma_f32 v[242:243], v[118:119], v[204:205], v[242:243] op_sel:[0,0,0] op_sel_hi:[1,0,1]
	v_pk_fma_f32 v[242:243], v[120:121], v[204:205], v[242:243] op_sel:[0,1,0] op_sel_hi:[1,1,1]
	v_pk_fma_f32 v[242:243], v[122:123], v[206:207], v[242:243] op_sel:[0,0,0] op_sel_hi:[1,0,1]
	v_pk_fma_f32 v[242:243], v[124:125], v[206:207], v[242:243] op_sel:[0,1,0] op_sel_hi:[1,1,1]
	v_fmac_f32_e32 v241, v126, v240
	v_pk_fma_f32 v[242:243], v[128:129], v[240:241], v[242:243] op_sel:[0,0,0] op_sel_hi:[1,0,1]
	v_pk_fma_f32 v[242:243], v[130:131], v[240:241], v[242:243] op_sel:[0,1,0] op_sel_hi:[1,1,1]
	v_fmac_f32_e32 v243, v127, v242
	v_cndmask_b32_e64 v200, v240, v84, s[98:99]
	v_cndmask_b32_e64 v201, v241, v85, s[98:99]
	v_cndmask_b32_e64 v202, v242, v86, s[98:99]
	v_cndmask_b32_e64 v203, v243, v87, s[98:99]
	v_mov_b32_e32 v252, v240
	v_mov_b32_e32 v253, v241
	v_mov_b32_e32 v254, v242
	v_mov_b32_e32 v255, v243
	v_mfma_f32_16x16x4_f32 v[208:211], v184, v200, v[208:211]
	v_mfma_f32_16x16x4_f32 v[212:215], v188, v200, v[212:215]
	v_mfma_f32_16x16x4_f32 v[216:219], v192, v200, v[216:219]
	v_mfma_f32_16x16x4_f32 v[220:223], v196, v200, v[220:223]
	v_permlane32_swap_b32_e32 v252, v254
	v_permlane32_swap_b32_e32 v253, v255
	v_mfma_f32_16x16x4_f32 v[208:211], v185, v201, v[208:211]
	v_mfma_f32_16x16x4_f32 v[212:215], v189, v201, v[212:215]
	v_mfma_f32_16x16x4_f32 v[216:219], v193, v201, v[216:219]
	v_mfma_f32_16x16x4_f32 v[220:223], v197, v201, v[220:223]
	v_mfma_f32_16x16x4_f32 v[208:211], v186, v202, v[208:211]
	v_mfma_f32_16x16x4_f32 v[212:215], v190, v202, v[212:215]
	v_mfma_f32_16x16x4_f32 v[216:219], v194, v202, v[216:219]
	v_mfma_f32_16x16x4_f32 v[220:223], v198, v202, v[220:223]
	v_mfma_f32_16x16x4_f32 v[208:211], v187, v203, v[208:211]
	v_mfma_f32_16x16x4_f32 v[212:215], v191, v203, v[212:215]
	v_mfma_f32_16x16x4_f32 v[216:219], v195, v203, v[216:219]
	v_mfma_f32_16x16x4_f32 v[220:223], v199, v203, v[220:223]
	v_mfma_f32_16x16x4_f32 v[248:251], v82, v252, v[240:243]
	v_mfma_f32_16x16x4_f32 v[248:251], v83, v253, v[248:251]
	s_waitcnt lgkmcnt(3)
	s_nop 4
	v_pk_mul_f32 v[208:209], v[208:209], v[88:89]
	v_pk_mul_f32 v[210:211], v[210:211], v[90:91]
	s_nop 0
	v_mfma_f32_16x16x4_f32 v[72:75], v140, v208, v[72:75]
	s_waitcnt lgkmcnt(2)
	v_pk_mul_f32 v[212:213], v[212:213], v[92:93]
	v_mfma_f32_16x16x4_f32 v[244:247], v141, v209, 0
	v_pk_mul_f32 v[214:215], v[214:215], v[94:95]
	v_mfma_f32_16x16x4_f32 v[72:75], v142, v210, v[72:75]
	s_waitcnt lgkmcnt(1)
	v_pk_mul_f32 v[216:217], v[216:217], v[96:97]
	v_mfma_f32_16x16x4_f32 v[244:247], v143, v211, v[244:247]
	v_pk_mul_f32 v[218:219], v[218:219], v[98:99]
	v_mfma_f32_16x16x4_f32 v[72:75], v144, v212, v[72:75]
	s_waitcnt lgkmcnt(0)
	v_pk_mul_f32 v[220:221], v[220:221], v[100:101]
	v_mfma_f32_16x16x4_f32 v[244:247], v145, v213, v[244:247]
	v_pk_mul_f32 v[222:223], v[222:223], v[102:103]
	v_mfma_f32_16x16x4_f32 v[72:75], v146, v214, v[72:75]
	s_mov_b64 exec, s[98:99]
	ds_write_b32 v231, v248
	ds_write_b32 v231, v249 offset:256
	ds_write_b32 v231, v250 offset:512
	ds_write_b32 v231, v251 offset:768
	s_mov_b64 exec, -1
	ds_read_b128 v[184:187], v236 offset:14080
	ds_read_b128 v[188:191], v236 offset:15104
	v_mfma_f32_16x16x4_f32 v[244:247], v147, v215, v[244:247]
	ds_read_b128 v[192:195], v236 offset:16128
	ds_read_b128 v[196:199], v236 offset:17152
	v_mfma_f32_16x16x4_f32 v[72:75], v148, v216, v[72:75]
	ds_read_b64 v[80:81], v32
	ds_read_b64 v[82:83], v33
	ds_read_b32 v84, v230 offset:4096
	ds_read_b32 v85, v230 offset:4352
	v_mfma_f32_16x16x4_f32 v[244:247], v149, v217, v[244:247]
	ds_read_b32 v86, v230 offset:4608
	ds_read_b32 v87, v230 offset:4864
	ds_read_b32 v36, v239 offset:4096
	ds_read_b32 v37, v239 offset:4352
	v_mfma_f32_16x16x4_f32 v[72:75], v150, v218, v[72:75]
	ds_read_b128 v[88:91], v26
	ds_read_b128 v[92:95], v26 offset:1024
	ds_read_b128 v[96:99], v26 offset:2048
	ds_read_b128 v[100:103], v26 offset:3072
	v_mfma_f32_16x16x4_f32 v[244:247], v151, v219, v[244:247]
	ds_read_b32 v104, v29 offset:4
	ds_read_b32 v105, v29 offset:76
	ds_read_b64 v[106:107], v29 offset:8
	ds_read_b64 v[108:109], v29 offset:40
	v_mfma_f32_16x16x4_f32 v[72:75], v152, v220, v[72:75]
	ds_read_b32 v126, v31 offset:4
	ds_read_b32 v127, v31 offset:76
	ds_read_b64 v[128:129], v31 offset:8
	ds_read_b64 v[130:131], v31 offset:40
	v_mfma_f32_16x16x4_f32 v[244:247], v153, v221, v[244:247]
	ds_read_b64 v[110:111], v30
	ds_read_b64 v[112:113], v30 offset:32
	ds_read_b64 v[114:115], v30 offset:64
	ds_read_b64 v[116:117], v30 offset:96
	v_mfma_f32_16x16x4_f32 v[72:75], v154, v222, v[72:75]
	ds_read_b64 v[118:119], v30 offset:8
	ds_read_b64 v[120:121], v30 offset:40
	ds_read_b64 v[122:123], v30 offset:72
	ds_read_b64 v[124:125], v30 offset:104
	v_mfma_f32_16x16x4_f32 v[244:247], v155, v223, v[244:247]
	s_nop 9
	v_pk_add_f32 v[72:73], v[72:73], v[244:245]
	v_pk_add_f32 v[74:75], v[74:75], v[246:247]
	v_fmac_f32_e32 v73, v156, v72
	v_pk_fma_f32 v[74:75], v[158:159], v[72:73], v[74:75] op_sel:[0,0,0] op_sel_hi:[1,0,1]
	v_pk_fma_f32 v[74:75], v[160:161], v[72:73], v[74:75] op_sel:[0,1,0] op_sel_hi:[1,1,1]
	v_fmac_f32_e32 v75, v157, v74
	ds_bpermute_b32 v204, v232, v72
	ds_bpermute_b32 v205, v232, v73
	ds_bpermute_b32 v206, v232, v74
	ds_bpermute_b32 v207, v232, v75
	ds_read_b128 v[140:143], v226 offset:9984
	ds_read_b128 v[144:147], v226 offset:10048
	ds_read_b128 v[148:151], v226 offset:10112
	ds_read_b128 v[152:155], v226 offset:10176
	s_waitcnt lgkmcnt(15)
	v_mfma_f32_16x16x4_f32 v[240:243], v80, v36, 0
	v_mfma_f32_16x16x4_f32 v[240:243], v81, v37, v[240:243]
	s_waitcnt lgkmcnt(6)
	v_pk_fma_f32 v[72:73], v[162:163], v[204:205], v[72:73] op_sel:[0,0,0] op_sel_hi:[1,0,1]
	v_pk_fma_f32 v[72:73], v[164:165], v[204:205], v[72:73] op_sel:[0,1,0] op_sel_hi:[1,1,1]
	s_waitcnt lgkmcnt(4)
	v_pk_fma_f32 v[72:73], v[166:167], v[206:207], v[72:73] op_sel:[0,0,0] op_sel_hi:[1,0,1]
	v_pk_fma_f32 v[72:73], v[168:169], v[206:207], v[72:73] op_sel:[0,1,0] op_sel_hi:[1,1,1]
	v_pk_fma_f32 v[74:75], v[170:171], v[204:205], v[74:75] op_sel:[0,0,0] op_sel_hi:[1,0,1]
	v_pk_fma_f32 v[74:75], v[172:173], v[204:205], v[74:75] op_sel:[0,1,0] op_sel_hi:[1,1,1]
	v_pk_fma_f32 v[74:75], v[174:175], v[206:207], v[74:75] op_sel:[0,0,0] op_sel_hi:[1,0,1]
	v_pk_fma_f32 v[74:75], v[176:177], v[206:207], v[74:75] op_sel:[0,1,0] op_sel_hi:[1,1,1]
	v_fmac_f32_e32 v73, v178, v72
	v_pk_fma_f32 v[74:75], v[180:181], v[72:73], v[74:75] op_sel:[0,0,0] op_sel_hi:[1,0,1]
	v_pk_fma_f32 v[74:75], v[182:183], v[72:73], v[74:75] op_sel:[0,1,0] op_sel_hi:[1,1,1]
	v_fmac_f32_e32 v75, v179, v74
	v_cndmask_b32_e64 v200, v72, v136, s[98:99]
	v_cndmask_b32_e64 v201, v73, v137, s[98:99]
	v_cndmask_b32_e64 v202, v74, v138, s[98:99]
	v_cndmask_b32_e64 v203, v75, v139, s[98:99]
	v_mov_b32_e32 v252, v72
	v_mov_b32_e32 v253, v73
	v_mov_b32_e32 v254, v74
	v_mov_b32_e32 v255, v75
	v_mfma_f32_16x16x4_f32 v[208:211], v184, v200, v[208:211]
	v_mfma_f32_16x16x4_f32 v[212:215], v188, v200, v[212:215]
	v_mfma_f32_16x16x4_f32 v[216:219], v192, v200, v[216:219]
	v_mfma_f32_16x16x4_f32 v[220:223], v196, v200, v[220:223]
	v_permlane32_swap_b32_e32 v252, v254
	v_permlane32_swap_b32_e32 v253, v255
	v_mfma_f32_16x16x4_f32 v[208:211], v185, v201, v[208:211]
	v_mfma_f32_16x16x4_f32 v[212:215], v189, v201, v[212:215]
	v_mfma_f32_16x16x4_f32 v[216:219], v193, v201, v[216:219]
	v_mfma_f32_16x16x4_f32 v[220:223], v197, v201, v[220:223]
	v_mfma_f32_16x16x4_f32 v[208:211], v186, v202, v[208:211]
	v_mfma_f32_16x16x4_f32 v[212:215], v190, v202, v[212:215]
	v_mfma_f32_16x16x4_f32 v[216:219], v194, v202, v[216:219]
	v_mfma_f32_16x16x4_f32 v[220:223], v198, v202, v[220:223]
	v_mfma_f32_16x16x4_f32 v[208:211], v187, v203, v[208:211]
	v_mfma_f32_16x16x4_f32 v[212:215], v191, v203, v[212:215]
	v_mfma_f32_16x16x4_f32 v[216:219], v195, v203, v[216:219]
	v_mfma_f32_16x16x4_f32 v[220:223], v199, v203, v[220:223]
	v_mfma_f32_16x16x4_f32 v[248:251], v134, v252, v[72:75]
	v_mfma_f32_16x16x4_f32 v[248:251], v135, v253, v[248:251]
	s_waitcnt lgkmcnt(3)
	s_nop 4
	v_pk_mul_f32 v[208:209], v[208:209], v[140:141]
	v_pk_mul_f32 v[210:211], v[210:211], v[142:143]
	s_nop 0
	v_mfma_f32_16x16x4_f32 v[240:243], v88, v208, v[240:243]
	s_waitcnt lgkmcnt(2)
	v_pk_mul_f32 v[212:213], v[212:213], v[144:145]
	v_mfma_f32_16x16x4_f32 v[244:247], v89, v209, 0
	v_pk_mul_f32 v[214:215], v[214:215], v[146:147]
	v_mfma_f32_16x16x4_f32 v[240:243], v90, v210, v[240:243]
	s_waitcnt lgkmcnt(1)
	v_pk_mul_f32 v[216:217], v[216:217], v[148:149]
	v_mfma_f32_16x16x4_f32 v[244:247], v91, v211, v[244:247]
	v_pk_mul_f32 v[218:219], v[218:219], v[150:151]
	v_mfma_f32_16x16x4_f32 v[240:243], v92, v212, v[240:243]
	s_waitcnt lgkmcnt(0)
	v_pk_mul_f32 v[220:221], v[220:221], v[152:153]
	v_mfma_f32_16x16x4_f32 v[244:247], v93, v213, v[244:247]
	v_pk_mul_f32 v[222:223], v[222:223], v[154:155]
	v_mfma_f32_16x16x4_f32 v[240:243], v94, v214, v[240:243]
	s_mov_b64 exec, s[98:99]
	ds_write_b32 v231, v248 offset:2048
	ds_write_b32 v231, v249 offset:2304
	ds_write_b32 v231, v250 offset:2560
	ds_write_b32 v231, v251 offset:2816
	s_mov_b64 exec, -1
	ds_read_b128 v[184:187], v27 offset:4096
	ds_read_b128 v[188:191], v27 offset:5120
	v_mfma_f32_16x16x4_f32 v[244:247], v95, v215, v[244:247]
	ds_read_b128 v[192:195], v27 offset:6144
	ds_read_b128 v[196:199], v27 offset:7168
	v_mfma_f32_16x16x4_f32 v[240:243], v96, v216, v[240:243]
	ds_read_b64 v[132:133], v32 offset:9984
	ds_read_b64 v[134:135], v33 offset:9984
	ds_read_b32 v136, v230 offset:6144
	ds_read_b32 v137, v230 offset:6400
	v_mfma_f32_16x16x4_f32 v[244:247], v97, v217, v[244:247]
	ds_read_b32 v138, v230 offset:6656
	ds_read_b32 v139, v230 offset:6912
	ds_read_b32 v38, v239 offset:6144
	ds_read_b32 v39, v239 offset:6400
	v_mfma_f32_16x16x4_f32 v[240:243], v98, v218, v[240:243]
	ds_read_b128 v[140:143], v26 offset:9984
	ds_read_b128 v[144:147], v26 offset:11008
	ds_read_b128 v[148:151], v26 offset:12032
	ds_read_b128 v[152:155], v26 offset:13056
	v_mfma_f32_16x16x4_f32 v[244:247], v99, v219, v[244:247]
	ds_read_b32 v156, v29 offset:9988
	ds_read_b32 v157, v29 offset:10060
	ds_read_b64 v[158:159], v29 offset:9992
	ds_read_b64 v[160:161], v29 offset:10024
	v_mfma_f32_16x16x4_f32 v[240:243], v100, v220, v[240:243]
	ds_read_b32 v178, v31 offset:9988
	ds_read_b32 v179, v31 offset:10060
	ds_read_b64 v[180:181], v31 offset:9992
	ds_read_b64 v[182:183], v31 offset:10024
	v_mfma_f32_16x16x4_f32 v[244:247], v101, v221, v[244:247]
	ds_read_b64 v[162:163], v30 offset:9984
	ds_read_b64 v[164:165], v30 offset:10016
	ds_read_b64 v[166:167], v30 offset:10048
	ds_read_b64 v[168:169], v30 offset:10080
	v_mfma_f32_16x16x4_f32 v[240:243], v102, v222, v[240:243]
	ds_read_b64 v[170:171], v30 offset:9992
	ds_read_b64 v[172:173], v30 offset:10024
	ds_read_b64 v[174:175], v30 offset:10056
	ds_read_b64 v[176:177], v30 offset:10088
	v_mfma_f32_16x16x4_f32 v[244:247], v103, v223, v[244:247]
	s_nop 9
	v_pk_add_f32 v[240:241], v[240:241], v[244:245]
	v_pk_add_f32 v[242:243], v[242:243], v[246:247]
	v_fmac_f32_e32 v241, v104, v240
	v_pk_fma_f32 v[242:243], v[106:107], v[240:241], v[242:243] op_sel:[0,0,0] op_sel_hi:[1,0,1]
	v_pk_fma_f32 v[242:243], v[108:109], v[240:241], v[242:243] op_sel:[0,1,0] op_sel_hi:[1,1,1]
	v_fmac_f32_e32 v243, v105, v242
	ds_bpermute_b32 v204, v232, v240
	ds_bpermute_b32 v205, v232, v241
	ds_bpermute_b32 v206, v232, v242
	ds_bpermute_b32 v207, v232, v243
	ds_read_b128 v[88:91], v28
	ds_read_b128 v[92:95], v28 offset:64
	ds_read_b128 v[96:99], v28 offset:128
	ds_read_b128 v[100:103], v28 offset:192
	s_waitcnt lgkmcnt(15)
	v_mfma_f32_16x16x4_f32 v[72:75], v132, v38, 0
	v_mfma_f32_16x16x4_f32 v[72:75], v133, v39, v[72:75]
	s_waitcnt lgkmcnt(6)
	v_pk_fma_f32 v[240:241], v[110:111], v[204:205], v[240:241] op_sel:[0,0,0] op_sel_hi:[1,0,1]
	v_pk_fma_f32 v[240:241], v[112:113], v[204:205], v[240:241] op_sel:[0,1,0] op_sel_hi:[1,1,1]
	s_waitcnt lgkmcnt(4)
	v_pk_fma_f32 v[240:241], v[114:115], v[206:207], v[240:241] op_sel:[0,0,0] op_sel_hi:[1,0,1]
	v_pk_fma_f32 v[240:241], v[116:117], v[206:207], v[240:241] op_sel:[0,1,0] op_sel_hi:[1,1,1]
	v_pk_fma_f32 v[242:243], v[118:119], v[204:205], v[242:243] op_sel:[0,0,0] op_sel_hi:[1,0,1]
	v_pk_fma_f32 v[242:243], v[120:121], v[204:205], v[242:243] op_sel:[0,1,0] op_sel_hi:[1,1,1]
	v_pk_fma_f32 v[242:243], v[122:123], v[206:207], v[242:243] op_sel:[0,0,0] op_sel_hi:[1,0,1]
	v_pk_fma_f32 v[242:243], v[124:125], v[206:207], v[242:243] op_sel:[0,1,0] op_sel_hi:[1,1,1]
	v_fmac_f32_e32 v241, v126, v240
	v_pk_fma_f32 v[242:243], v[128:129], v[240:241], v[242:243] op_sel:[0,0,0] op_sel_hi:[1,0,1]
	v_pk_fma_f32 v[242:243], v[130:131], v[240:241], v[242:243] op_sel:[0,1,0] op_sel_hi:[1,1,1]
	v_fmac_f32_e32 v243, v127, v242
	v_cndmask_b32_e64 v200, v240, v84, s[98:99]
	v_cndmask_b32_e64 v201, v241, v85, s[98:99]
	v_cndmask_b32_e64 v202, v242, v86, s[98:99]
	v_cndmask_b32_e64 v203, v243, v87, s[98:99]
	v_mov_b32_e32 v252, v240
	v_mov_b32_e32 v253, v241
	v_mov_b32_e32 v254, v242
	v_mov_b32_e32 v255, v243
	v_mfma_f32_16x16x4_f32 v[208:211], v184, v200, v[208:211]
	v_mfma_f32_16x16x4_f32 v[212:215], v188, v200, v[212:215]
	v_mfma_f32_16x16x4_f32 v[216:219], v192, v200, v[216:219]
	v_mfma_f32_16x16x4_f32 v[220:223], v196, v200, v[220:223]
	v_permlane32_swap_b32_e32 v252, v254
	v_permlane32_swap_b32_e32 v253, v255
	v_mfma_f32_16x16x4_f32 v[208:211], v185, v201, v[208:211]
	v_mfma_f32_16x16x4_f32 v[212:215], v189, v201, v[212:215]
	v_mfma_f32_16x16x4_f32 v[216:219], v193, v201, v[216:219]
	v_mfma_f32_16x16x4_f32 v[220:223], v197, v201, v[220:223]
	v_mfma_f32_16x16x4_f32 v[208:211], v186, v202, v[208:211]
	v_mfma_f32_16x16x4_f32 v[212:215], v190, v202, v[212:215]
	v_mfma_f32_16x16x4_f32 v[216:219], v194, v202, v[216:219]
	v_mfma_f32_16x16x4_f32 v[220:223], v198, v202, v[220:223]
	v_mfma_f32_16x16x4_f32 v[208:211], v187, v203, v[208:211]
	v_mfma_f32_16x16x4_f32 v[212:215], v191, v203, v[212:215]
	v_mfma_f32_16x16x4_f32 v[216:219], v195, v203, v[216:219]
	v_mfma_f32_16x16x4_f32 v[220:223], v199, v203, v[220:223]
	v_mfma_f32_16x16x4_f32 v[248:251], v82, v252, v[240:243]
	v_mfma_f32_16x16x4_f32 v[248:251], v83, v253, v[248:251]
	s_waitcnt lgkmcnt(3)
	s_nop 4
	v_pk_mul_f32 v[208:209], v[208:209], v[88:89]
	v_pk_mul_f32 v[210:211], v[210:211], v[90:91]
	s_nop 0
	v_mfma_f32_16x16x4_f32 v[72:75], v140, v208, v[72:75]
	s_waitcnt lgkmcnt(2)
	v_pk_mul_f32 v[212:213], v[212:213], v[92:93]
	v_mfma_f32_16x16x4_f32 v[244:247], v141, v209, 0
	v_pk_mul_f32 v[214:215], v[214:215], v[94:95]
	v_mfma_f32_16x16x4_f32 v[72:75], v142, v210, v[72:75]
	s_waitcnt lgkmcnt(1)
	v_pk_mul_f32 v[216:217], v[216:217], v[96:97]
	v_mfma_f32_16x16x4_f32 v[244:247], v143, v211, v[244:247]
	v_pk_mul_f32 v[218:219], v[218:219], v[98:99]
	v_mfma_f32_16x16x4_f32 v[72:75], v144, v212, v[72:75]
	s_waitcnt lgkmcnt(0)
	v_pk_mul_f32 v[220:221], v[220:221], v[100:101]
	v_mfma_f32_16x16x4_f32 v[244:247], v145, v213, v[244:247]
	v_pk_mul_f32 v[222:223], v[222:223], v[102:103]
	v_mfma_f32_16x16x4_f32 v[72:75], v146, v214, v[72:75]
	s_mov_b64 exec, s[98:99]
	ds_write_b32 v231, v248 offset:4096
	ds_write_b32 v231, v249 offset:4352
	ds_write_b32 v231, v250 offset:4608
	ds_write_b32 v231, v251 offset:4864
	s_mov_b64 exec, -1
	ds_read_b128 v[184:187], v27 offset:14080
	ds_read_b128 v[188:191], v27 offset:15104
	v_mfma_f32_16x16x4_f32 v[244:247], v147, v215, v[244:247]
	ds_read_b128 v[192:195], v27 offset:16128
	ds_read_b128 v[196:199], v27 offset:17152
	v_mfma_f32_16x16x4_f32 v[72:75], v148, v216, v[72:75]
	v_mfma_f32_16x16x4_f32 v[244:247], v149, v217, v[244:247]
	v_mfma_f32_16x16x4_f32 v[72:75], v150, v218, v[72:75]
	v_mfma_f32_16x16x4_f32 v[244:247], v151, v219, v[244:247]
	v_mfma_f32_16x16x4_f32 v[72:75], v152, v220, v[72:75]
	v_mfma_f32_16x16x4_f32 v[244:247], v153, v221, v[244:247]
	v_mfma_f32_16x16x4_f32 v[72:75], v154, v222, v[72:75]
	v_mfma_f32_16x16x4_f32 v[244:247], v155, v223, v[244:247]
	s_nop 9
	v_pk_add_f32 v[72:73], v[72:73], v[244:245]
	v_pk_add_f32 v[74:75], v[74:75], v[246:247]
	v_fmac_f32_e32 v73, v156, v72
	v_pk_fma_f32 v[74:75], v[158:159], v[72:73], v[74:75] op_sel:[0,0,0] op_sel_hi:[1,0,1]
	v_pk_fma_f32 v[74:75], v[160:161], v[72:73], v[74:75] op_sel:[0,1,0] op_sel_hi:[1,1,1]
	v_fmac_f32_e32 v75, v157, v74
	ds_bpermute_b32 v204, v232, v72
	ds_bpermute_b32 v205, v232, v73
	ds_bpermute_b32 v206, v232, v74
	ds_bpermute_b32 v207, v232, v75
	ds_read_b128 v[140:143], v28 offset:9984
	ds_read_b128 v[144:147], v28 offset:10048
	ds_read_b128 v[148:151], v28 offset:10112
	ds_read_b128 v[152:155], v28 offset:10176
	s_waitcnt lgkmcnt(6)
	v_pk_fma_f32 v[72:73], v[162:163], v[204:205], v[72:73] op_sel:[0,0,0] op_sel_hi:[1,0,1]
	v_pk_fma_f32 v[72:73], v[164:165], v[204:205], v[72:73] op_sel:[0,1,0] op_sel_hi:[1,1,1]
	s_waitcnt lgkmcnt(4)
	v_pk_fma_f32 v[72:73], v[166:167], v[206:207], v[72:73] op_sel:[0,0,0] op_sel_hi:[1,0,1]
	v_pk_fma_f32 v[72:73], v[168:169], v[206:207], v[72:73] op_sel:[0,1,0] op_sel_hi:[1,1,1]
	v_pk_fma_f32 v[74:75], v[170:171], v[204:205], v[74:75] op_sel:[0,0,0] op_sel_hi:[1,0,1]
	v_pk_fma_f32 v[74:75], v[172:173], v[204:205], v[74:75] op_sel:[0,1,0] op_sel_hi:[1,1,1]
	v_pk_fma_f32 v[74:75], v[174:175], v[206:207], v[74:75] op_sel:[0,0,0] op_sel_hi:[1,0,1]
	v_pk_fma_f32 v[74:75], v[176:177], v[206:207], v[74:75] op_sel:[0,1,0] op_sel_hi:[1,1,1]
	v_fmac_f32_e32 v73, v178, v72
	v_pk_fma_f32 v[74:75], v[180:181], v[72:73], v[74:75] op_sel:[0,0,0] op_sel_hi:[1,0,1]
	v_pk_fma_f32 v[74:75], v[182:183], v[72:73], v[74:75] op_sel:[0,1,0] op_sel_hi:[1,1,1]
	v_fmac_f32_e32 v75, v179, v74
	v_cndmask_b32_e64 v200, v72, v136, s[98:99]
	v_cndmask_b32_e64 v201, v73, v137, s[98:99]
	v_cndmask_b32_e64 v202, v74, v138, s[98:99]
	v_cndmask_b32_e64 v203, v75, v139, s[98:99]
	v_mov_b32_e32 v252, v72
	v_mov_b32_e32 v253, v73
	v_mov_b32_e32 v254, v74
	v_mov_b32_e32 v255, v75
	v_mfma_f32_16x16x4_f32 v[208:211], v184, v200, v[208:211]
	v_mfma_f32_16x16x4_f32 v[212:215], v188, v200, v[212:215]
	v_mfma_f32_16x16x4_f32 v[216:219], v192, v200, v[216:219]
	v_mfma_f32_16x16x4_f32 v[220:223], v196, v200, v[220:223]
	v_permlane32_swap_b32_e32 v252, v254
	v_permlane32_swap_b32_e32 v253, v255
	v_mfma_f32_16x16x4_f32 v[208:211], v185, v201, v[208:211]
	v_mfma_f32_16x16x4_f32 v[212:215], v189, v201, v[212:215]
	v_mfma_f32_16x16x4_f32 v[216:219], v193, v201, v[216:219]
	v_mfma_f32_16x16x4_f32 v[220:223], v197, v201, v[220:223]
	v_mfma_f32_16x16x4_f32 v[208:211], v186, v202, v[208:211]
	v_mfma_f32_16x16x4_f32 v[212:215], v190, v202, v[212:215]
	v_mfma_f32_16x16x4_f32 v[216:219], v194, v202, v[216:219]
	v_mfma_f32_16x16x4_f32 v[220:223], v198, v202, v[220:223]
	v_mfma_f32_16x16x4_f32 v[208:211], v187, v203, v[208:211]
	v_mfma_f32_16x16x4_f32 v[212:215], v191, v203, v[212:215]
	v_mfma_f32_16x16x4_f32 v[216:219], v195, v203, v[216:219]
	v_mfma_f32_16x16x4_f32 v[220:223], v199, v203, v[220:223]
	v_mfma_f32_16x16x4_f32 v[248:251], v134, v252, v[72:75]
	v_mfma_f32_16x16x4_f32 v[248:251], v135, v253, v[248:251]
	s_waitcnt lgkmcnt(3)
	s_nop 4
	v_pk_mul_f32 v[208:209], v[208:209], v[140:141]
	v_pk_mul_f32 v[210:211], v[210:211], v[142:143]
	s_waitcnt lgkmcnt(2)
	v_pk_mul_f32 v[212:213], v[212:213], v[144:145]
	v_pk_mul_f32 v[214:215], v[214:215], v[146:147]
	s_waitcnt lgkmcnt(1)
	v_pk_mul_f32 v[216:217], v[216:217], v[148:149]
	v_pk_mul_f32 v[218:219], v[218:219], v[150:151]
	s_waitcnt lgkmcnt(0)
	v_pk_mul_f32 v[220:221], v[220:221], v[152:153]
	v_pk_mul_f32 v[222:223], v[222:223], v[154:155]
	s_mov_b64 exec, s[98:99]
	ds_write_b32 v231, v248 offset:6144
	ds_write_b32 v231, v249 offset:6400
	ds_write_b32 v231, v250 offset:6656
	ds_write_b32 v231, v251 offset:6912
	s_mov_b64 exec, -1
	s_branch .LBB0_655
